# Hyena FFT: nt on the once-read conv-input / filter-tap loads (keep the per-workgroup kernel-spectrum scratch L2-resident), on top of P6 residual nt
# speedup vs baseline: 1.0173x; 1.0084x over previous
.LBB0_424:
	v_ashrrev_i32_e32 v3, 31, v2
	v_lshlrev_b64 v[4:5], 1, v[2:3]
	v_lshl_add_u64 v[6:7], s[78:79], 0, v[4:5]
	global_load_dwordx2 v[14:15], v[6:7], off nt
	v_lshl_add_u64 v[6:7], s[80:81], 0, v[4:5]
	global_load_dwordx2 v[16:17], v[6:7], off nt
	v_lshl_add_u64 v[6:7], s[86:87], 0, v[4:5]
	v_lshl_add_u64 v[12:13], s[82:83], 0, v[4:5]
	global_load_dwordx2 v[4:5], v[6:7], off nt
	s_nop 0
	global_load_dwordx2 v[6:7], v[12:13], off nt
	v_ashrrev_i32_e32 v11, 9, v2
	v_and_b32_e32 v12, -16, v2
	v_add_u32_e32 v3, s23, v10
	v_lshl_add_u32 v11, v11, 7, v12
	v_add3_u32 v11, 0, v11, v8
	v_cmp_ne_u32_e32 vcc, 0, v3
	s_waitcnt vmcnt(3)
	v_lshlrev_b32_e32 v12, 16, v14
	v_and_b32_e32 v14, 0xffff0000, v14
	v_lshlrev_b32_e32 v30, 16, v15
	v_and_b32_e32 v32, 0xffff0000, v15
	s_waitcnt vmcnt(2)
	v_lshlrev_b32_e32 v13, 16, v16
	v_and_b32_e32 v15, 0xffff0000, v16
	v_lshlrev_b32_e32 v31, 16, v17
	v_and_b32_e32 v33, 0xffff0000, v17
	ds_write_b128 v11, v[12:15]
	ds_write_b128 v11, v[30:33] offset:16
	s_and_saveexec_b64 s[88:89], vcc
	s_xor_b64 s[88:89], exec, s[88:89]
	s_cbranch_execz .LBB0_426
	v_add_u32_e32 v11, 0x4000, v3
	v_ashrrev_i32_e32 v14, 9, v11
	v_lshlrev_b32_e32 v14, 7, v14
	v_and_b32_e32 v11, -16, v11
	v_add3_u32 v11, v14, v11, 0
	s_waitcnt vmcnt(1)
	v_lshlrev_b32_e32 v13, 16, v4
	s_waitcnt vmcnt(0)
	v_lshlrev_b32_e32 v12, 16, v6
	v_add3_u32 v11, v11, v9, s96
	ds_write_b64 v11, v[12:13]

.LBB0_434:
	v_add_u32_e32 v16, s23, v26
	v_ashrrev_i32_e32 v17, 31, v16
	v_lshl_add_u64 v[2:3], v[16:17], 1, s[86:87]
	v_lshl_add_u64 v[32:33], v[16:17], 1, s[88:89]
	global_load_dwordx4 v[6:9], v[2:3], off nt
	v_cmp_lt_i32_e32 vcc, 0, v16
	v_mov_b32_e32 v29, 0
	v_mov_b32_e32 v30, 0
	v_mov_b32_e32 v17, 0
	v_mov_b32_e32 v31, 0
	v_cmp_gt_i32_e64 s[6:7], s5, v16
	s_and_saveexec_b64 s[92:93], vcc
	global_load_ushort v30, v[2:3], off offset:-2 nt
	global_load_ushort v31, v[32:33], off offset:-2 nt
	s_mov_b64 exec, s[92:93]
	s_nop 0
	s_and_saveexec_b64 s[92:93], s[6:7]
	global_load_ushort v29, v[2:3], off offset:16 nt
	global_load_ushort v17, v[32:33], off offset:16 nt
	s_mov_b64 exec, s[92:93]
	s_nop 0
	global_load_dwordx4 v[2:5], v[32:33], off nt
	s_waitcnt vmcnt(1)
	v_lshlrev_b32_e32 v30, 16, v30
	v_lshlrev_b32_e32 v29, 16, v29
	v_lshlrev_b32_e32 v31, 16, v31
	v_lshlrev_b32_e32 v17, 16, v17
	s_branch .LBB0_433

.LBB0_446:
	v_add_u32_e32 v14, s23, v29
	v_ashrrev_i32_e32 v15, 31, v14
	v_lshl_add_u64 v[2:3], v[14:15], 1, s[84:85]
	v_lshl_add_u64 v[16:17], v[14:15], 1, s[86:87]
	global_load_dwordx4 v[6:9], v[2:3], off nt
	v_cmp_lt_i32_e32 vcc, 0, v14
	v_mov_b32_e32 v30, 0
	v_mov_b32_e32 v32, 0
	v_mov_b32_e32 v15, 0
	v_mov_b32_e32 v31, 0
	v_cmp_gt_i32_e64 s[6:7], s5, v14
	s_and_saveexec_b64 s[90:91], vcc
	global_load_ushort v32, v[2:3], off offset:-2 nt
	global_load_ushort v31, v[16:17], off offset:-2 nt
	s_mov_b64 exec, s[90:91]
	s_nop 0
	s_and_saveexec_b64 s[90:91], s[6:7]
	global_load_ushort v30, v[2:3], off offset:16 nt
	global_load_ushort v15, v[16:17], off offset:16 nt
	s_mov_b64 exec, s[90:91]
	s_nop 0
	global_load_dwordx4 v[2:5], v[16:17], off nt
	s_waitcnt vmcnt(1)
	v_lshlrev_b32_e32 v32, 16, v32
	v_lshlrev_b32_e32 v30, 16, v30
	v_lshlrev_b32_e32 v31, 16, v31
	v_lshlrev_b32_e32 v15, 16, v15
	s_branch .LBB0_445

.LBB0_458:
	v_add_u32_e32 v14, s6, v30
	v_ashrrev_i32_e32 v15, 31, v14
	v_lshl_add_u64 v[2:3], v[14:15], 1, s[76:77]
	v_lshl_add_u64 v[28:29], v[14:15], 1, s[80:81]
	global_load_dwordx4 v[6:9], v[2:3], off nt
	v_cmp_lt_i32_e32 vcc, 0, v14
	v_mov_b32_e32 v16, 0
	v_mov_b32_e32 v32, 0
	v_mov_b32_e32 v17, 0
	v_mov_b32_e32 v31, 0
	v_cmp_gt_i32_e64 s[6:7], s5, v14
	s_and_saveexec_b64 s[86:87], vcc
	global_load_ushort v32, v[2:3], off offset:-2 nt
	global_load_ushort v31, v[28:29], off offset:-2 nt
	s_mov_b64 exec, s[86:87]
	s_nop 0
	s_and_saveexec_b64 s[86:87], s[6:7]
	global_load_ushort v16, v[2:3], off offset:16 nt
	global_load_ushort v17, v[28:29], off offset:16 nt
	s_mov_b64 exec, s[86:87]
	s_nop 0
	global_load_dwordx4 v[2:5], v[28:29], off nt
	s_waitcnt vmcnt(1)
	v_lshlrev_b32_e32 v32, 16, v32
	v_lshlrev_b32_e32 v16, 16, v16
	v_lshlrev_b32_e32 v31, 16, v31
	v_lshlrev_b32_e32 v17, 16, v17
	s_branch .LBB0_457
